# adds: HGRN state-update waves write the bf16 state with 2 ds_write_b128 (half-wave pieces paired by permlane32 swaps) instead of 4 ds_write_b64
# baseline (speedup 1.0000x reference)
.LBB0_633:
	s_andn2_b64 vcc, exec, s[14:15]
	v_add_u32_e32 v78, v46, v51
	s_cbranch_vccnz .LBB0_635
	s_waitcnt lgkmcnt(2)
	ds_read_b128 v[80:83], v59 offset:8704
	ds_read_b128 v[84:87], v78 offset:12800
	ds_read_b128 v[104:107], v60 offset:13824
	ds_read_b128 v[108:111], v60 offset:13856
	ds_read_b128 v[112:115], v60 offset:13888
	ds_read_b128 v[116:119], v60 offset:13920
	s_waitcnt lgkmcnt(4)
	v_mfma_f32_32x32x16_bf16 v[4:19], v[80:83], v[84:87], v[4:19]
	s_waitcnt lgkmcnt(0)
	s_nop 10
	v_pk_mul_f32 v[4:5], v[4:5], v[104:105]
	v_pk_mul_f32 v[6:7], v[6:7], v[106:107]
	v_pk_mul_f32 v[8:9], v[8:9], v[108:109]
	v_pk_mul_f32 v[10:11], v[10:11], v[110:111]
	v_pk_mul_f32 v[12:13], v[12:13], v[112:113]
	v_pk_mul_f32 v[14:15], v[14:15], v[114:115]
	v_pk_mul_f32 v[16:17], v[16:17], v[116:117]
	v_pk_mul_f32 v[18:19], v[18:19], v[118:119]
	v_bfe_u32 v188, v234, 5, 1
	v_cvt_pk_bf16_f32 v80, v4, v5
	v_cvt_pk_bf16_f32 v81, v6, v7
	v_cvt_pk_bf16_f32 v82, v8, v9
	v_cvt_pk_bf16_f32 v83, v10, v11
	v_cvt_pk_bf16_f32 v84, v12, v13
	v_cvt_pk_bf16_f32 v85, v14, v15
	v_cvt_pk_bf16_f32 v86, v16, v17
	v_cvt_pk_bf16_f32 v87, v18, v19
	v_lshl_add_u32 v188, v188, 3, v61
	v_permlane32_swap_b32_e32 v80, v82
	v_permlane32_swap_b32_e32 v81, v83
	v_permlane32_swap_b32_e32 v84, v86
	v_permlane32_swap_b32_e32 v85, v87
	ds_write_b128 v188, v[80:83] offset:28672
	ds_write_b128 v188, v[84:87] offset:28704

.LBB0_646:
	s_waitcnt lgkmcnt(2)
	ds_read_b128 v[80:83], v59 offset:23040
	ds_read_b128 v[84:87], v78 offset:27136
	ds_read_b128 v[104:107], v60 offset:28160
	ds_read_b128 v[108:111], v60 offset:28192
	ds_read_b128 v[112:115], v60 offset:28224
	ds_read_b128 v[116:119], v60 offset:28256
	s_waitcnt lgkmcnt(4)
	v_mfma_f32_32x32x16_bf16 v[4:19], v[80:83], v[84:87], v[4:19]
	s_waitcnt lgkmcnt(0)
	s_nop 10
	v_pk_mul_f32 v[4:5], v[4:5], v[104:105]
	v_pk_mul_f32 v[6:7], v[6:7], v[106:107]
	v_pk_mul_f32 v[8:9], v[8:9], v[108:109]
	v_pk_mul_f32 v[10:11], v[10:11], v[110:111]
	v_pk_mul_f32 v[12:13], v[12:13], v[112:113]
	v_pk_mul_f32 v[14:15], v[14:15], v[114:115]
	v_pk_mul_f32 v[16:17], v[16:17], v[116:117]
	v_pk_mul_f32 v[18:19], v[18:19], v[118:119]
	v_bfe_u32 v188, v234, 5, 1
	v_cvt_pk_bf16_f32 v80, v4, v5
	v_cvt_pk_bf16_f32 v81, v6, v7
	v_cvt_pk_bf16_f32 v82, v8, v9
	v_cvt_pk_bf16_f32 v83, v10, v11
	v_cvt_pk_bf16_f32 v84, v12, v13
	v_cvt_pk_bf16_f32 v85, v14, v15
	v_cvt_pk_bf16_f32 v86, v16, v17
	v_cvt_pk_bf16_f32 v87, v18, v19
	v_lshl_add_u32 v188, v188, 3, v61
	v_permlane32_swap_b32_e32 v80, v82
	v_permlane32_swap_b32_e32 v81, v83
	v_permlane32_swap_b32_e32 v84, v86
	v_permlane32_swap_b32_e32 v85, v87
	ds_write_b128 v188, v[80:83] offset:37376
	ds_write_b128 v188, v[84:87] offset:37408
	s_branch .LBB0_624
